# S5 items remapped so each XCD handles 4 adjacent state-space groups (shared tables and cache lines stay in one L2); lprep rmsnorm row loop param loads hoisted; s5 Toeplitz table copy unrolled
# speedup vs baseline: 1.0563x; 1.0062x over previous
; __device__ __forceinline__ unsigned cvt_pk_bf16(float lo, float hi) { unsigned r; asm("v_cvt_pk_bf16_f32 %0, %1, %2" : "=v"(r) : "v"(lo), "v"(hi)); return r; }
; #define mod ((const float*)(getp().ws + O_MOD))
; #define hL (layer == 0 ? getp().in[0] : (const float*)getp().out)
; #define hC (layer == 0 ? getp().in[2] : (const float*)hctx)
; __device__ __forceinline__ void xn_row(const float* hrow, const float* g, const float* shift, const float* scale, bf16_t* orow, int lane) {
;     const float4* xr = (const float4*)hrow + lane;
;     float4 v[8]; float s = 0.f;
; #pragma unroll
;     for (int j = 0; j < 8; ++j) { v[j] = xr[64 * j]; s += v[j].x * v[j].x + v[j].y * v[j].y + v[j].z * v[j].z + v[j].w * v[j].w; }
;     const float r = rsqrtf(wave_sum(s) * (1.f / D) + 1e-6f);
;     u32x2* o = (u32x2*)orow + lane;
; #pragma unroll
;     for (int j = 0; j < 8; ++j) { const float4 gg = ((const float4*)g)[lane + 64 * j], sh = ((const float4*)shift)[lane + 64 * j], sc = ((const float4*)scale)[lane + 64 * j];
;         u32x2 w; w.x = cvt_pk_bf16(v[j].x * r * gg.x * (1.f + sc.x) + sh.x, v[j].y * r * gg.y * (1.f + sc.y) + sh.y);
;         w.y = cvt_pk_bf16(v[j].z * r * gg.z * (1.f + sc.z) + sh.z, v[j].w * r * gg.w * (1.f + sc.w) + sh.w);
;         o[64 * j] = w; }
; }
; __device__ __forceinline__ void xn_row1(PRef p, int layer, int which  , int row, int lane, const float* hL, const float* hC) {
;     const float* mod = (const float*)(p.ws + O_MOD);
;     const bool isc = row >= RL; const int mr = isc ? 4 : (row >> 12);
;     const float* m = mod + (size_t)(layer * 5 + mr) * 12288 + (which ? 3 * 2048 : 0);
;     const float* hrow = isc ? hC + (size_t)(row - RL) * 2048 : hL + (size_t)row * 2048;
;     xn_row(hrow, p.in[which ? 29 : 6] + layer * 2048, m, m + 2048, (bf16_t*)(p.ws + O_XN) + (size_t)row * 2048, lane);
.LBB0_214:
	s_or_b64 exec, exec, s[18:19]
	v_lshl_add_u64 v[0:1], v[0:1], 0, v[42:43]
	global_load_dwordx4 v[70:73], v[0:1], off
	global_load_dwordx4 v[74:77], v[0:1], off offset:1024
	global_load_dwordx4 v[20:23], v[0:1], off offset:2048
	global_load_dwordx4 v[16:19], v[0:1], off offset:3072
	v_add_co_u32_e32 v56, vcc, s13, v0
	v_min_i32_e32 v55, 0x4000, v24
	s_nop 0
	v_addc_co_u32_e32 v57, vcc, 0, v1, vcc
	global_load_dwordx4 v[12:15], v[56:57], off
	global_load_dwordx4 v[8:11], v[56:57], off offset:1024
	global_load_dwordx4 v[4:7], v[56:57], off offset:2048
	global_load_dwordx4 v[0:3], v[56:57], off offset:3072
	v_ashrrev_i32_e32 v55, 12, v55
	v_mul_hi_i32_i24_e32 v57, 0xc000, v55
	v_mul_i32_i24_e32 v56, 0xc000, v55
	v_lshl_add_u64 v[56:57], s[6:7], 0, v[56:57]
	v_lshl_add_u64 v[60:61], v[56:57], 0, s[16:17]
	v_lshl_add_u64 v[90:91], v[56:57], 0, v[42:43]
	global_load_dwordx4 v[78:81], v[30:31], off
	v_lshl_add_u64 v[92:93], v[60:61], 0, v[42:43]
	global_load_dwordx4 v[82:85], v[90:91], off
	global_load_dwordx4 v[86:89], v[92:93], off
	global_load_dwordx4 v[116:119], v[30:31], off offset:1024
	v_add_co_u32_e32 v114, vcc, v44, v60
	s_nop 1
	v_addc_co_u32_e32 v115, vcc, 0, v61, vcc
	global_load_dwordx4 v[120:123], v[114:115], off
	v_add_co_u32_e32 v114, vcc, v44, v56
	s_nop 1
	v_addc_co_u32_e32 v115, vcc, 0, v57, vcc
	global_load_dwordx4 v[124:127], v[114:115], off
	global_load_dwordx4 v[128:131], v[30:31], off offset:2048
	v_add_co_u32_e32 v114, vcc, v46, v60
	s_nop 1
	v_addc_co_u32_e32 v115, vcc, 0, v61, vcc
	global_load_dwordx4 v[132:135], v[114:115], off
	v_add_co_u32_e32 v114, vcc, v46, v56
	s_nop 1
	v_addc_co_u32_e32 v115, vcc, 0, v57, vcc
	global_load_dwordx4 v[136:139], v[114:115], off
	global_load_dwordx4 v[140:143], v[30:31], off offset:3072
	v_add_co_u32_e32 v114, vcc, v48, v60
	s_nop 1
	v_addc_co_u32_e32 v115, vcc, 0, v61, vcc
	global_load_dwordx4 v[144:147], v[114:115], off
	v_add_co_u32_e32 v114, vcc, v48, v56
	s_nop 1
	v_addc_co_u32_e32 v115, vcc, 0, v57, vcc
	global_load_dwordx4 v[148:151], v[114:115], off
	global_load_dwordx4 v[152:155], v[32:33], off
	v_add_co_u32_e32 v114, vcc, v50, v60
	s_nop 1
	v_addc_co_u32_e32 v115, vcc, 0, v61, vcc
	global_load_dwordx4 v[156:159], v[114:115], off
	v_add_co_u32_e32 v114, vcc, v50, v56
	s_nop 1
	v_addc_co_u32_e32 v115, vcc, 0, v57, vcc
	global_load_dwordx4 v[160:163], v[114:115], off
	global_load_dwordx4 v[164:167], v[34:35], off
	v_add_co_u32_e32 v114, vcc, v52, v60
	s_nop 1
	v_addc_co_u32_e32 v115, vcc, 0, v61, vcc
	global_load_dwordx4 v[168:171], v[114:115], off
	v_add_co_u32_e32 v114, vcc, v52, v56
	s_nop 1
	v_addc_co_u32_e32 v115, vcc, 0, v57, vcc
	global_load_dwordx4 v[172:175], v[114:115], off
	global_load_dwordx4 v[176:179], v[36:37], off
	v_add_co_u32_e32 v114, vcc, v26, v60
	s_nop 1
	v_addc_co_u32_e32 v115, vcc, 0, v61, vcc
	global_load_dwordx4 v[180:183], v[114:115], off
	v_add_co_u32_e32 v114, vcc, v26, v56
	s_nop 1
	v_addc_co_u32_e32 v115, vcc, 0, v57, vcc
	global_load_dwordx4 v[184:187], v[114:115], off
	global_load_dwordx4 v[188:191], v[38:39], off
	v_add_co_u32_e32 v114, vcc, v54, v60
	s_nop 1
	v_addc_co_u32_e32 v115, vcc, 0, v61, vcc
	global_load_dwordx4 v[192:195], v[114:115], off
	v_add_co_u32_e32 v114, vcc, v54, v56
	s_nop 1
	v_addc_co_u32_e32 v115, vcc, 0, v57, vcc
	global_load_dwordx4 v[196:199], v[114:115], off
	v_lshlrev_b64 v[58:59], 12, v[58:59]
	v_lshl_add_u64 v[58:59], v[28:29], 0, v[58:59]
	v_lshl_add_u64 v[24:25], v[24:25], 0, s[86:87]
	v_lshl_add_u64 v[40:41], v[40:41], 0, s[8:9]
	s_waitcnt vmcnt(31)
	v_mul_f32_e32 v55, v71, v71
	s_waitcnt vmcnt(30)
	v_mul_f32_e32 v69, v75, v75
	s_waitcnt vmcnt(29)
	v_mul_f32_e32 v108, v21, v21
	v_fmac_f32_e32 v55, v70, v70
	v_fmac_f32_e32 v69, v74, v74
	s_waitcnt vmcnt(28)
	v_mul_f32_e32 v109, v17, v17
	v_fmac_f32_e32 v108, v20, v20
	s_waitcnt vmcnt(27)
	v_mov_b32_e32 v94, v13
	s_waitcnt vmcnt(26)
	v_mov_b32_e32 v95, v9
	v_fmac_f32_e32 v55, v72, v72
	v_fmac_f32_e32 v69, v76, v76
	v_fmac_f32_e32 v109, v16, v16
	v_mov_b32_e32 v92, v12
	v_mov_b32_e32 v93, v8
	v_fmac_f32_e32 v108, v22, v22
	v_pk_mul_f32 v[94:95], v[94:95], v[94:95]
	v_fmac_f32_e32 v55, v73, v73
	v_fmac_f32_e32 v69, v77, v77
	v_mov_b32_e32 v96, v14
	v_mov_b32_e32 v97, v10
	s_waitcnt vmcnt(25)
	v_mov_b32_e32 v102, v5
	s_waitcnt vmcnt(24)
	v_mov_b32_e32 v103, v1
	v_fmac_f32_e32 v109, v18, v18
	v_fmac_f32_e32 v108, v23, v23
	v_pk_fma_f32 v[92:93], v[92:93], v[92:93], v[94:95]
	v_add_f32_e32 v55, v55, v69
	v_mov_b32_e32 v98, v15
	v_mov_b32_e32 v99, v11
	v_mov_b32_e32 v100, v4
	v_mov_b32_e32 v101, v0
	v_pk_mul_f32 v[102:103], v[102:103], v[102:103]
	v_fmac_f32_e32 v109, v19, v19
	v_pk_fma_f32 v[92:93], v[96:97], v[96:97], v[92:93]
	v_add_f32_e32 v55, v55, v108
	v_mov_b32_e32 v104, v6
	v_mov_b32_e32 v105, v2
	v_pk_fma_f32 v[94:95], v[100:101], v[100:101], v[102:103]
	v_pk_fma_f32 v[92:93], v[98:99], v[98:99], v[92:93]
	v_add_f32_e32 v55, v55, v109
	v_mov_b32_e32 v106, v7
	v_mov_b32_e32 v107, v3
	v_pk_fma_f32 v[94:95], v[104:105], v[104:105], v[94:95]
	v_add_f32_e32 v55, v55, v92
	v_pk_fma_f32 v[94:95], v[106:107], v[106:107], v[94:95]
	v_add_f32_e32 v55, v55, v93
	v_add_f32_e32 v55, v55, v94
	v_add_f32_e32 v55, v55, v95
	ds_bpermute_b32 v69, v62, v55
	s_waitcnt vmcnt(21)
	v_add_f32_e32 v86, 1.0, v86
	v_lshl_add_u64 v[92:93], v[60:61], 0, v[44:45]
	s_waitcnt lgkmcnt(0)
	v_add_f32_e32 v55, v55, v69
	ds_bpermute_b32 v69, v63, v55
	s_waitcnt lgkmcnt(0)
	v_add_f32_e32 v55, v55, v69
	ds_bpermute_b32 v69, v64, v55
	s_waitcnt lgkmcnt(0)
; __device__ __forceinline__ unsigned cvt_pk_bf16(float lo, float hi) { unsigned r; asm("v_cvt_pk_bf16_f32 %0, %1, %2" : "=v"(r) : "v"(lo), "v"(hi)); return r; }
; __device__ __forceinline__ void xn_row(const float* hrow, const float* g, const float* shift, const float* scale, bf16_t* orow, int lane) {
;     ...
;     const float r = rsqrtf(wave_sum(s) * (1.f / D) + 1e-6f);
;     u32x2* o = (u32x2*)orow + lane;
; #pragma unroll
;     for (int j = 0; j < 8; ++j) { const float4 gg = ((const float4*)g)[lane + 64 * j], sh = ((const float4*)shift)[lane + 64 * j], sc = ((const float4*)scale)[lane + 64 * j];
;         u32x2 w; w.x = cvt_pk_bf16(v[j].x * r * gg.x * (1.f + sc.x) + sh.x, v[j].y * r * gg.y * (1.f + sc.y) + sh.y);
;         w.y = cvt_pk_bf16(v[j].z * r * gg.z * (1.f + sc.z) + sh.z, v[j].w * r * gg.w * (1.f + sc.w) + sh.w);
;         o[64 * j] = w; }
	v_add_f32_e32 v55, v55, v69
	ds_bpermute_b32 v69, v65, v55
	s_waitcnt lgkmcnt(0)
	v_add_f32_e32 v55, v55, v69
	ds_bpermute_b32 v69, v66, v55
	s_waitcnt lgkmcnt(0)
	v_add_f32_e32 v55, v55, v69
	ds_bpermute_b32 v69, v67, v55
	s_waitcnt lgkmcnt(0)
	v_add_f32_e32 v55, v55, v69
	v_fmamk_f32 v55, v55, 0x3a000000, v68
	v_mul_f32_e32 v69, 0x4b800000, v55
	v_cmp_gt_f32_e32 vcc, s14, v55
	s_nop 1
	v_cndmask_b32_e32 v55, v55, v69, vcc
	v_rsq_f32_e32 v55, v55
	v_add_f32_e32 v69, 1.0, v87
	v_add_f32_e32 v87, 1.0, v88
	v_add_f32_e32 v88, 1.0, v89
	v_mul_f32_e32 v89, 0x45800000, v55
	v_cndmask_b32_e32 v89, v55, v89, vcc
	v_mul_f32_e32 v55, v70, v89
	v_mul_f32_e32 v70, v71, v89
	v_mul_f32_e32 v71, v72, v89
	v_mul_f32_e32 v72, v73, v89
	v_mul_f32_e32 v71, v80, v71
	v_mul_f32_e32 v55, v78, v55
	v_mul_f32_e32 v70, v79, v70
	v_mul_f32_e32 v72, v81, v72
	v_fma_f32 v71, v71, v87, v84
	v_fma_f32 v55, v86, v55, v82
	v_fma_f32 v69, v69, v70, v83
	v_fmac_f32_e32 v85, v72, v88
	v_cvt_pk_bf16_f32 v70, v55, v69
	v_cvt_pk_bf16_f32 v71, v71, v85
	global_store_dwordx2 v[58:59], v[70:71], off
	v_cmp_lt_i32_e32 vcc, s20, v24
	s_or_b64 s[10:11], vcc, s[10:11]
	v_mov_b32_e32 v55, v27
	v_mul_f32_e32 v74, v74, v89
	v_mul_f32_e32 v75, v75, v89
	v_mul_f32_e32 v76, v76, v89
	v_mul_f32_e32 v77, v77, v89
	v_mul_f32_e32 v20, v20, v89
	v_mul_f32_e32 v21, v21, v89
	v_mul_f32_e32 v22, v22, v89
	v_mul_f32_e32 v23, v23, v89
	v_mul_f32_e32 v16, v16, v89
	v_mul_f32_e32 v17, v17, v89
	v_mul_f32_e32 v18, v18, v89
	v_mul_f32_e32 v19, v19, v89
	v_mul_f32_e32 v12, v12, v89
	v_mul_f32_e32 v13, v13, v89
	v_mul_f32_e32 v14, v14, v89
	v_mul_f32_e32 v15, v15, v89
	v_mul_f32_e32 v8, v8, v89
	v_mul_f32_e32 v9, v9, v89
	v_mul_f32_e32 v10, v10, v89
	v_mul_f32_e32 v11, v11, v89
	v_mul_f32_e32 v4, v4, v89
	v_mul_f32_e32 v5, v5, v89
	v_mul_f32_e32 v6, v6, v89
	v_mul_f32_e32 v7, v7, v89
	v_mul_f32_e32 v0, v0, v89
	v_mul_f32_e32 v1, v1, v89
	v_mul_f32_e32 v2, v2, v89
	v_mul_f32_e32 v3, v3, v89
	s_waitcnt vmcnt(18)
	v_mul_f32_e32 v74, v74, v116
	v_mul_f32_e32 v75, v75, v117
	v_mul_f32_e32 v76, v76, v118
	v_mul_f32_e32 v77, v77, v119
	v_add_f32_e32 v120, 1.0, v120
	v_add_f32_e32 v121, 1.0, v121
	v_add_f32_e32 v122, 1.0, v122
	v_add_f32_e32 v123, 1.0, v123
	v_fma_f32 v74, v74, v120, v124
	v_fma_f32 v75, v75, v121, v125
	v_fma_f32 v76, v76, v122, v126
	v_fma_f32 v77, v77, v123, v127
	v_cvt_pk_bf16_f32 v74, v74, v75
	v_cvt_pk_bf16_f32 v75, v76, v77
	global_store_dwordx2 v[58:59], v[74:75], off offset:512
	s_waitcnt vmcnt(15)
	v_mul_f32_e32 v20, v20, v128
	v_mul_f32_e32 v21, v21, v129
	v_mul_f32_e32 v22, v22, v130
	v_mul_f32_e32 v23, v23, v131
	v_add_f32_e32 v132, 1.0, v132
	v_add_f32_e32 v133, 1.0, v133
	v_add_f32_e32 v134, 1.0, v134
	v_add_f32_e32 v135, 1.0, v135
	v_fma_f32 v20, v20, v132, v136
	v_fma_f32 v21, v21, v133, v137
	v_fma_f32 v22, v22, v134, v138
	v_fma_f32 v23, v23, v135, v139
	v_cvt_pk_bf16_f32 v20, v20, v21
	v_cvt_pk_bf16_f32 v21, v22, v23
	global_store_dwordx2 v[58:59], v[20:21], off offset:1024
	s_waitcnt vmcnt(12)
	v_mul_f32_e32 v16, v16, v140
	v_mul_f32_e32 v17, v17, v141
	v_mul_f32_e32 v18, v18, v142
	v_mul_f32_e32 v19, v19, v143
	v_add_f32_e32 v144, 1.0, v144
	v_add_f32_e32 v145, 1.0, v145
	v_add_f32_e32 v146, 1.0, v146
	v_add_f32_e32 v147, 1.0, v147
	v_fma_f32 v16, v16, v144, v148
	v_fma_f32 v17, v17, v145, v149
	v_fma_f32 v18, v18, v146, v150
	v_fma_f32 v19, v19, v147, v151
	v_cvt_pk_bf16_f32 v16, v16, v17
	v_cvt_pk_bf16_f32 v17, v18, v19
	global_store_dwordx2 v[58:59], v[16:17], off offset:1536
	s_waitcnt vmcnt(9)
	v_mul_f32_e32 v12, v12, v152
	v_mul_f32_e32 v13, v13, v153
	v_mul_f32_e32 v14, v14, v154
	v_mul_f32_e32 v15, v15, v155
	v_add_f32_e32 v156, 1.0, v156
	v_add_f32_e32 v157, 1.0, v157
	v_add_f32_e32 v158, 1.0, v158
	v_add_f32_e32 v159, 1.0, v159
	v_fma_f32 v12, v12, v156, v160
	v_fma_f32 v13, v13, v157, v161
	v_fma_f32 v14, v14, v158, v162
	v_fma_f32 v15, v15, v159, v163
	v_cvt_pk_bf16_f32 v12, v12, v13
	v_cvt_pk_bf16_f32 v13, v14, v15
	global_store_dwordx2 v[58:59], v[12:13], off offset:2048
	s_waitcnt vmcnt(6)
	v_mul_f32_e32 v8, v8, v164
	v_mul_f32_e32 v9, v9, v165
	v_mul_f32_e32 v10, v10, v166
	v_mul_f32_e32 v11, v11, v167
	v_add_f32_e32 v168, 1.0, v168
	v_add_f32_e32 v169, 1.0, v169
	v_add_f32_e32 v170, 1.0, v170
	v_add_f32_e32 v171, 1.0, v171
	v_fma_f32 v8, v8, v168, v172
	v_fma_f32 v9, v9, v169, v173
	v_fma_f32 v10, v10, v170, v174
	v_fma_f32 v11, v11, v171, v175
	v_cvt_pk_bf16_f32 v8, v8, v9
	v_cvt_pk_bf16_f32 v9, v10, v11
	global_store_dwordx2 v[58:59], v[8:9], off offset:2560
	s_waitcnt vmcnt(3)
	v_mul_f32_e32 v4, v4, v176
	v_mul_f32_e32 v5, v5, v177
	v_mul_f32_e32 v6, v6, v178
	v_mul_f32_e32 v7, v7, v179
	v_add_f32_e32 v180, 1.0, v180
	v_add_f32_e32 v181, 1.0, v181
	v_add_f32_e32 v182, 1.0, v182
	v_add_f32_e32 v183, 1.0, v183
	v_fma_f32 v4, v4, v180, v184
	v_fma_f32 v5, v5, v181, v185
	v_fma_f32 v6, v6, v182, v186
	v_fma_f32 v7, v7, v183, v187
	v_cvt_pk_bf16_f32 v4, v4, v5
	v_cvt_pk_bf16_f32 v5, v6, v7
	global_store_dwordx2 v[58:59], v[4:5], off offset:3072
	s_waitcnt vmcnt(0)
	v_mul_f32_e32 v0, v0, v188
	v_mul_f32_e32 v1, v1, v189
	v_mul_f32_e32 v2, v2, v190
	v_mul_f32_e32 v3, v3, v191
	v_add_f32_e32 v192, 1.0, v192
	v_add_f32_e32 v193, 1.0, v193
	v_add_f32_e32 v194, 1.0, v194
	v_add_f32_e32 v195, 1.0, v195
	v_fma_f32 v0, v0, v192, v196
	v_fma_f32 v1, v1, v193, v197
	v_fma_f32 v2, v2, v194, v198
	v_fma_f32 v3, v3, v195, v199
	v_cvt_pk_bf16_f32 v0, v0, v1
	v_cvt_pk_bf16_f32 v1, v2, v3
	global_store_dwordx2 v[58:59], v[0:1], off offset:3584
	s_andn2_b64 exec, exec, s[10:11]
	s_cbranch_execz .LBB0_217

; __device__ __forceinline__ int otid() { int t = (int)__builtin_amdgcn_workitem_id_x(); asm volatile("" : "+v"(t)); return t; }
; __device__ __forceinline__ void s5inc_item(PRef p, int item, unsigned char* shm) {
;     const int tid = otid(), lane = tid & 63, wave = tid >> 6, fr = lane & 15, fq = lane >> 4;
;     const int g = item >> 3, dir = (item >> 2) & 1, b = item & 3;
;     const bf16_t* A = (const bf16_t*)(p.ws + O_A);
;     const bf16_t* E = (const bf16_t*)(p.ws + O_S5E) + ((size_t)(dir * 32 + g) * 128 + 16 * wave + fr) * 1024 + fq * 8;
;     bf16x8 af[32];
; #pragma unroll
;     for (int kk = 0; kk < 32; ++kk) af[kk] = *(const bf16x8*)(E + kk * 32);
;     float* ST = (float*)(p.ws + O_S5ST) + (size_t)((g * 2 + dir) * 4 + b) * 68 * 128;
.LBB0_262:
	s_and_b64 vcc, exec, s[2:3]
	s_cbranch_vccz .LBB0_256
	s_and_b32 s99, s39, 7
	s_lshl_b32 s99, s99, 2
	s_lshr_b32 s100, s39, 6
	s_add_i32 s99, s99, s100
	s_lshl_b32 s99, s99, 3
	s_bfe_u32 s100, s39, 0x30003
	s_or_b32 s99, s99, s100
	s_bfe_u32 s4, s99, 0x10002
	s_ashr_i32 s12, s99, 3
	s_lshl_b32 s2, s4, 5
	v_mov_b32_e32 v134, v222
	s_add_i32 s2, s2, s12
	s_ashr_i32 s3, s2, 31
	v_ashrrev_i32_e32 v0, 2, v134
	v_and_b32_e32 v128, -16, v0
	s_lshl_b64 s[2:3], s[2:3], 7
	v_ashrrev_i32_e32 v129, 31, v128
	v_and_b32_e32 v147, 15, v134
	v_lshl_add_u64 v[0:1], s[2:3], 0, v[128:129]
	v_or_b32_e32 v0, v0, v147
	v_lshlrev_b64 v[0:1], 11, v[0:1]
	v_lshl_add_u64 v[0:1], s[20:21], 0, v[0:1]
	v_and_b32_e32 v130, 48, v134
	v_mov_b32_e32 v131, v133
	v_lshl_add_u64 v[124:125], v[0:1], 0, v[130:131]
	global_load_dwordx4 v[0:3], v[124:125], off
	global_load_dwordx4 v[4:7], v[124:125], off offset:64
	global_load_dwordx4 v[8:11], v[124:125], off offset:128
	global_load_dwordx4 v[12:15], v[124:125], off offset:192
	global_load_dwordx4 v[16:19], v[124:125], off offset:256
	global_load_dwordx4 v[20:23], v[124:125], off offset:320
	global_load_dwordx4 v[24:27], v[124:125], off offset:384
	global_load_dwordx4 v[28:31], v[124:125], off offset:448
	global_load_dwordx4 v[32:35], v[124:125], off offset:512
	global_load_dwordx4 v[36:39], v[124:125], off offset:576
	global_load_dwordx4 v[40:43], v[124:125], off offset:640
	global_load_dwordx4 v[44:47], v[124:125], off offset:704
	global_load_dwordx4 v[48:51], v[124:125], off offset:768
	global_load_dwordx4 v[52:55], v[124:125], off offset:832
	global_load_dwordx4 v[56:59], v[124:125], off offset:896
	global_load_dwordx4 v[60:63], v[124:125], off offset:960
	global_load_dwordx4 v[64:67], v[124:125], off offset:1024
	global_load_dwordx4 v[68:71], v[124:125], off offset:1088
	global_load_dwordx4 v[72:75], v[124:125], off offset:1152
	global_load_dwordx4 v[76:79], v[124:125], off offset:1216
	global_load_dwordx4 v[80:83], v[124:125], off offset:1280
	global_load_dwordx4 v[84:87], v[124:125], off offset:1344
	global_load_dwordx4 v[88:91], v[124:125], off offset:1408
	global_load_dwordx4 v[92:95], v[124:125], off offset:1472
	global_load_dwordx4 v[96:99], v[124:125], off offset:1536
	global_load_dwordx4 v[100:103], v[124:125], off offset:1600
	global_load_dwordx4 v[104:107], v[124:125], off offset:1664
	global_load_dwordx4 v[108:111], v[124:125], off offset:1728
	global_load_dwordx4 v[112:115], v[124:125], off offset:1792
	global_load_dwordx4 v[116:119], v[124:125], off offset:1856
	global_load_dwordx4 v[120:123], v[124:125], off offset:1920
	s_nop 0
	global_load_dwordx4 v[124:127], v[124:125], off offset:1984
	s_and_b32 s2, s99, 3
	s_and_b32 s3, s99, -8
	s_lshl_b32 s4, s4, 2
	s_lshl_b32 s24, s2, 12
	s_and_b32 s2, s99, 3
	s_or_b32 s3, s4, s3
	v_ashrrev_i32_e32 v149, 7, v134
	s_or_b32 s3, s3, s2
	v_lshlrev_b32_e32 v156, 6, v149
	v_mul_lo_u32 v157, v149, s37
	v_add_u32_e32 v149, 0x200, v134
	s_mul_hi_i32 s5, s3, 0x8800
	s_mul_i32 s3, s3, 0x8800
	v_and_b32_e32 v135, 1, v134
	v_bfe_u32 v155, v134, 1, 6
	v_ashrrev_i32_e32 v150, 7, v149
	s_add_u32 s4, s26, s3
	v_lshlrev_b32_e32 v132, 3, v135
	v_lshlrev_b32_e32 v148, 5, v155
	v_lshlrev_b32_e32 v135, 4, v135
	v_lshlrev_b32_e32 v154, 6, v150
	v_mul_lo_u32 v158, v150, s37
	v_add_u32_e32 v150, 0x400, v134
	v_add_u32_e32 v134, 0x600, v134
	s_addc_u32 s5, s27, s5
	v_add3_u32 v159, 0, v148, v135
	v_lshl_or_b32 v135, s2, 8, v155
	v_ashrrev_i32_e32 v151, 7, v150
	v_ashrrev_i32_e32 v134, 7, v134
	v_or_b32_e32 v135, 0x4000, v135
	v_lshlrev_b32_e32 v153, 6, v151
	v_lshlrev_b32_e32 v152, 6, v134
	v_lshl_add_u64 v[128:129], v[128:129], 2, s[4:5]
	v_and_or_b32 v148, v156, s36, v135
	v_and_or_b32 v149, v154, s36, v135
	v_and_or_b32 v150, v153, s36, v135
	v_mul_lo_u32 v160, v151, s37
	v_and_or_b32 v151, v152, s36, v135
	v_mul_lo_u32 v161, v134, s37
	v_lshl_add_u64 v[134:135], v[128:129], 0, v[130:131]
	v_add_u32_e32 v128, s24, v152
	v_or_b32_e32 v152, v128, v155
	v_add_u32_e32 v128, s24, v153
	s_lshl_b32 s22, s12, 4
	v_or_b32_e32 v153, v128, v155
	v_add_u32_e32 v128, s24, v154
	s_ashr_i32 s23, s22, 31
	v_mad_u32_u24 v162, v147, s37, 0
	v_or_b32_e32 v154, v128, v155
	v_add_u32_e32 v128, s24, v156
	s_mov_b32 s10, 4
	v_cmp_gt_u32_e64 s[2:3], 4, v147
	v_or_b32_e32 v155, v128, v155
	s_mov_b32 s12, 0
	s_lshl_b64 s[22:23], s[22:23], 1
	v_lshlrev_b32_e32 v132, 1, v132
	v_add_u32_e32 v156, v159, v157
	v_add_u32_e32 v157, v159, v158
	v_add_u32_e32 v158, v159, v160
	v_add_u32_e32 v159, v159, v161
	v_add_u32_e32 v160, v162, v130
	s_branch .LBB0_265

; __device__ __forceinline__ int otid() { int t = (int)__builtin_amdgcn_workitem_id_x(); asm volatile("" : "+v"(t)); return t; }
; __device__ __forceinline__ void s5out_item(PRef p, int layer, int item, unsigned char* shm) {
;     const int tid = otid(), lane = tid & 63, wave = tid >> 6, fr = lane & 15, fq = lane >> 4;
;     const int g = item >> 3, b = (item >> 1) & 3, mh = item & 1;
;     const bf16_t* A = (const bf16_t*)(p.ws + O_A);
;     bf16_t* KT = (bf16_t*)shm;
;     unsigned char* ul = shm + 65024;
;     __syncthreads();
;     { const u32x4* src = (const u32x4*)((const bf16_t*)(p.ws + O_S5K) + (size_t)g * 127 * 256); u32x4* dst = (u32x4*)shm;
;       for (int i = tid; i < 127 * 256 / 8; i += 512) dst[i] = src[i]; }
;     const int tb = 32 * mh + 4 * wave;
;     bf16_t* Z = (bf16_t*)(p.ws + O_Z5);
;     const f32x4 dv = *(const f32x4*)(p.in[25] + layer * 512 + g * 16 + fq * 4);
.LBB0_410:
	s_and_b64 vcc, exec, s[2:3]
	s_cbranch_vccz .LBB0_402
	s_and_b32 s99, s66, 7
	s_lshl_b32 s99, s99, 2
	s_lshr_b32 s100, s66, 6
	s_add_i32 s99, s99, s100
	s_lshl_b32 s99, s99, 3
	s_bfe_u32 s100, s66, 0x30003
	s_or_b32 s99, s99, s100
	s_ashr_i32 s2, s99, 3
	v_mov_b32_e32 v4, v222
	s_ashr_i32 s3, s2, 31
	s_nop 0
	v_cmp_gt_i32_e32 vcc, s61, v4
	s_barrier
	s_and_saveexec_b64 s[4:5], vcc
	s_cbranch_execz .LBB0_414
	s_mul_i32 s22, s2, 0xfe00
	s_mul_hi_i32 s12, s2, 0xfe00
	s_add_u32 s44, s34, s22
	v_ashrrev_i32_e32 v5, 31, v4
	s_addc_u32 s45, s35, s12
	v_add_u32_e32 v2, 0xfffffe00, v4
	v_lshl_add_u32 v3, v4, 4, 0
	v_lshl_add_u64 v[0:1], v[4:5], 4, s[44:45]
	s_mov_b64 s[44:45], 0
.LBB0_413:
	global_load_dwordx4 v[6:9], v[0:1], off
	v_lshl_add_u64 v[0:1], v[0:1], 0, s[24:25]
	global_load_dwordx4 v[148:151], v[0:1], off
	v_lshl_add_u64 v[0:1], v[0:1], 0, s[24:25]
	global_load_dwordx4 v[152:155], v[0:1], off
	v_lshl_add_u64 v[0:1], v[0:1], 0, s[24:25]
	global_load_dwordx4 v[156:159], v[0:1], off
	v_lshl_add_u64 v[0:1], v[0:1], 0, s[24:25]
	global_load_dwordx4 v[160:163], v[0:1], off
	v_lshl_add_u64 v[0:1], v[0:1], 0, s[24:25]
	global_load_dwordx4 v[164:167], v[0:1], off
	v_lshl_add_u64 v[0:1], v[0:1], 0, s[24:25]
	global_load_dwordx4 v[168:171], v[0:1], off
	v_lshl_add_u64 v[0:1], v[0:1], 0, s[24:25]
	v_add_u32_e32 v2, 0xe00, v2
	v_cmp_lt_i32_e32 vcc, s62, v2
	s_mov_b64 s[44:45], exec
	s_andn2_b64 exec, exec, vcc
	global_load_dwordx4 v[172:175], v[0:1], off
	s_mov_b64 exec, s[44:45]
	s_waitcnt vmcnt(7)
	ds_write_b128 v3, v[6:9]
	v_add_u32_e32 v3, 0x2000, v3
	s_waitcnt vmcnt(6)
	ds_write_b128 v3, v[148:151]
	v_add_u32_e32 v3, 0x2000, v3
	s_waitcnt vmcnt(5)
	ds_write_b128 v3, v[152:155]
	v_add_u32_e32 v3, 0x2000, v3
	s_waitcnt vmcnt(4)
	ds_write_b128 v3, v[156:159]
	v_add_u32_e32 v3, 0x2000, v3
	s_waitcnt vmcnt(3)
	ds_write_b128 v3, v[160:163]
	v_add_u32_e32 v3, 0x2000, v3
	s_waitcnt vmcnt(2)
	ds_write_b128 v3, v[164:167]
	v_add_u32_e32 v3, 0x2000, v3
	s_waitcnt vmcnt(1)
	ds_write_b128 v3, v[168:171]
	v_add_u32_e32 v3, 0x2000, v3
	s_waitcnt vmcnt(0)
	s_andn2_b64 exec, exec, vcc
	ds_write_b128 v3, v[172:175]
	s_mov_b64 exec, s[44:45]
.LBB0_414:
	s_or_b64 exec, exec, s[4:5]
	s_lshl_b32 s4, s99, 5
	s_and_b32 s22, s4, 32
	s_lshl_b32 s4, s2, 4
	s_ashr_i32 s5, s4, 31
	s_bfe_u32 s12, s99, 0x20001
	s_lshl_b64 s[44:45], s[4:5], 2
	s_add_u32 s50, s10, s44
	v_bfe_u32 v7, v4, 4, 2
	v_ashrrev_i32_e32 v9, 4, v4
	s_addc_u32 s51, s11, s45
	v_and_b32_e32 v0, -4, v9
	v_lshlrev_b32_e32 v6, 4, v7
	v_add_u32_e32 v63, s22, v0
	global_load_dwordx4 v[0:3], v6, s[50:51]
	v_and_b32_e32 v10, 1, v4
	v_bfe_u32 v11, v4, 1, 6
	s_lshl_b32 s67, s12, 8
	s_lshl_b32 s72, s12, 12
	v_lshlrev_b32_e32 v8, 3, v10
	v_lshlrev_b32_e32 v12, 5, v11
	v_lshlrev_b32_e32 v10, 4, v10
	v_add3_u32 v42, 0, v12, v10
	v_or_b32_e32 v10, s67, v11
	v_or_b32_e32 v64, s72, v11
	v_ashrrev_i32_e32 v11, 7, v4
	v_lshlrev_b32_e32 v65, 6, v11
	v_mul_lo_u32 v43, v11, s64
	v_add_u32_e32 v11, 0x200, v4
	v_ashrrev_i32_e32 v11, 7, v11
	v_lshlrev_b32_e32 v67, 6, v11
	v_mul_lo_u32 v44, v11, s64
	v_add_u32_e32 v11, 0x400, v4
	s_and_b32 s44, s99, -8
	v_ashrrev_i32_e32 v11, 7, v11
	s_or_b32 s12, s12, s44
	s_lshl_b64 s[44:45], s[4:5], 1
	v_lshlrev_b32_e32 v69, 6, v11
	v_mul_lo_u32 v45, v11, s64
	v_add_u32_e32 v11, 0x600, v4
	s_add_u32 s4, s31, s44
	v_ashrrev_i32_e32 v11, 7, v11
	s_addc_u32 s5, s33, s45
	v_and_b32_e32 v5, 15, v4
	v_or_b32_e32 v10, 0x4000, v10
	v_lshlrev_b32_e32 v71, 6, v11
	v_lshlrev_b32_e32 v32, 3, v7
	s_lshl_b64 s[68:69], s[2:3], 18
	s_lshl_b64 s[70:71], s[2:3], 18
	s_or_b32 s2, s12, 4
	v_and_or_b32 v66, v65, s63, v10
	v_and_or_b32 v68, v67, s63, v10
	v_and_or_b32 v70, v69, s63, v10
	v_and_or_b32 v72, v71, s63, v10
	v_mul_lo_u32 v46, v11, s64
	v_mul_u32_u24_e32 v47, 0x810, v5
	v_lshlrev_b32_e32 v10, 5, v7
	v_mov_b32_e32 v11, v33
	v_mov_b32_e32 v7, v33
	v_lshl_add_u64 v[22:23], s[4:5], 0, v[32:33]
	v_lshl_or_b32 v14, v63, 4, v5
	s_add_i32 s4, 0, 0xfe00
	s_mul_hi_i32 s49, s2, 0x8800
	s_mul_i32 s48, s2, 0x8800
	s_lshl_b32 s2, s99, 14
	v_lshl_add_u64 v[20:21], s[20:21], 0, v[10:11]
	v_lshl_add_u64 v[10:11], s[18:19], 0, v[6:7]
	v_lshlrev_b32_e32 v12, 6, v5
	v_ashrrev_i32_e32 v15, 31, v14
	v_add3_u32 v80, v47, v6, s4
	v_lshlrev_b32_e32 v6, 9, v9
	s_mul_hi_i32 s47, s12, 0x8800
	s_mul_i32 s46, s12, 0x8800
	s_and_b32 s12, s2, 0x4000
	v_add_u32_e32 v13, s67, v12
	v_lshlrev_b64 v[16:17], 8, v[14:15]
	v_or_b32_e32 v18, 16, v14
	v_or_b32_e32 v28, 32, v14
	v_or_b32_e32 v14, 48, v14
	v_and_b32_e32 v6, 0xfffff800, v6
	v_lshlrev_b32_e32 v48, 5, v5
	v_and_b32_e32 v74, 3, v4
	v_or_b32_e32 v75, 0x4000, v13
	v_or_b32_e32 v76, s72, v12
	v_lshl_add_u64 v[12:13], v[10:11], 0, s[68:69]
	v_ashrrev_i32_e32 v19, 31, v18
	v_ashrrev_i32_e32 v29, 31, v28
	v_ashrrev_i32_e32 v15, 31, v14
	v_lshl_add_u64 v[10:11], v[10:11], 0, s[70:71]
	v_add_u32_e32 v6, s12, v6
	v_and_b32_e32 v9, 16, v4
	v_lshlrev_b32_e32 v4, 4, v4
	v_lshlrev_b64 v[18:19], 8, v[18:19]
	v_lshlrev_b64 v[38:39], 8, v[28:29]
	v_lshlrev_b64 v[14:15], 8, v[14:15]
	v_lshl_add_u64 v[10:11], v[10:11], 0, s[42:43]
	v_or_b32_e32 v77, 1, v63
	v_or_b32_e32 v78, 2, v63
	v_or_b32_e32 v79, 3, v63
	v_or3_b32 v6, v6, v48, v9
	v_and_b32_e32 v4, 0x200, v4
	v_add_u32_e32 v73, 4, v5
	v_cmp_gt_u32_e64 s[2:3], 4, v5
	v_add3_u32 v7, 0, v47, v32
	v_lshl_add_u64 v[24:25], v[12:13], 0, v[16:17]
	v_lshl_add_u64 v[26:27], v[12:13], 0, v[18:19]
	v_lshl_add_u64 v[28:29], v[12:13], 0, v[38:39]
	v_lshl_add_u64 v[30:31], v[12:13], 0, v[14:15]
	v_lshl_add_u64 v[34:35], v[10:11], 0, v[16:17]
	v_lshl_add_u64 v[36:37], v[10:11], 0, v[18:19]
	v_lshl_add_u64 v[38:39], v[10:11], 0, v[38:39]
	v_lshl_add_u64 v[40:41], v[10:11], 0, v[14:15]
	v_lshlrev_b32_e32 v5, 5, v63
	v_lshlrev_b32_e32 v10, 5, v77
	v_lshlrev_b32_e32 v11, 5, v78
	v_lshlrev_b32_e32 v12, 5, v79
	v_sub_u32_e32 v4, v6, v4
	v_add_u32_e32 v81, 0, v4
	s_mov_b32 s22, 0
	v_lshlrev_b32_e32 v32, 1, v8
	v_add_u32_e32 v82, v42, v43
	v_add_u32_e32 v83, v42, v44
	v_add_u32_e32 v84, v42, v45
	v_add_u32_e32 v85, v42, v46
	v_add_u32_e32 v86, v7, v5
	v_add_u32_e32 v87, v7, v10
	v_add_u32_e32 v88, v7, v11
	v_add_u32_e32 v89, v7, v12
	s_branch .LBB0_416

; __device__ __forceinline__ unsigned cvt_pk_bf16(float lo, float hi) { unsigned r; asm("v_cvt_pk_bf16_f32 %0, %1, %2" : "=v"(r) : "v"(lo), "v"(hi)); return r; }
; __device__ __forceinline__ void xn_row(const float* hrow, const float* g, const float* shift, const float* scale, bf16_t* orow, int lane) {
;     const float4* xr = (const float4*)hrow + lane;
;     float4 v[8]; float s = 0.f;
; #pragma unroll
;     for (int j = 0; j < 8; ++j) { v[j] = xr[64 * j]; s += v[j].x * v[j].x + v[j].y * v[j].y + v[j].z * v[j].z + v[j].w * v[j].w; }
;     const float r = rsqrtf(wave_sum(s) * (1.f / D) + 1e-6f);
;     u32x2* o = (u32x2*)orow + lane;
; #pragma unroll
;     for (int j = 0; j < 8; ++j) { const float4 gg = ((const float4*)g)[lane + 64 * j], sh = ((const float4*)shift)[lane + 64 * j], sc = ((const float4*)scale)[lane + 64 * j];
;         u32x2 w; w.x = cvt_pk_bf16(v[j].x * r * gg.x * (1.f + sc.x) + sh.x, v[j].y * r * gg.y * (1.f + sc.y) + sh.y);
;         w.y = cvt_pk_bf16(v[j].z * r * gg.z * (1.f + sc.z) + sh.z, v[j].w * r * gg.w * (1.f + sc.w) + sh.w);
;         o[64 * j] = w; }
; }
.LBB0_767:
	s_or_b64 exec, exec, s[20:21]
	v_lshl_add_u64 v[0:1], v[0:1], 0, v[30:31]
	global_load_dwordx4 v[80:83], v[0:1], off
	global_load_dwordx4 v[24:27], v[0:1], off offset:1024
	global_load_dwordx4 v[20:23], v[0:1], off offset:2048
	global_load_dwordx4 v[16:19], v[0:1], off offset:3072
	v_add_co_u32_e32 v66, vcc, s3, v0
	v_min_i32_e32 v53, 0x4000, v28
	s_nop 0
	v_addc_co_u32_e32 v67, vcc, 0, v1, vcc
	global_load_dwordx4 v[12:15], v[66:67], off
	global_load_dwordx4 v[8:11], v[66:67], off offset:1024
	global_load_dwordx4 v[4:7], v[66:67], off offset:2048
	global_load_dwordx4 v[0:3], v[66:67], off offset:3072
	v_ashrrev_i32_e32 v53, 12, v53
	v_add_u32_e32 v53, 5, v53
	v_mul_hi_i32_i24_e32 v67, 0xc000, v53
	v_mul_i32_i24_e32 v66, 0xc000, v53
	v_lshl_add_u64 v[66:67], s[8:9], 0, v[66:67]
	v_lshl_add_u64 v[68:69], v[66:67], 0, s[10:11]
	v_lshl_add_u64 v[96:97], v[66:67], 0, v[30:31]
	global_load_dwordx4 v[84:87], v[34:35], off
	v_lshl_add_u64 v[98:99], v[68:69], 0, v[30:31]
	global_load_dwordx4 v[88:91], v[96:97], off
	global_load_dwordx4 v[92:95], v[98:99], off
	global_load_dwordx4 v[116:119], v[36:37], off
	v_add_co_u32_e32 v114, vcc, v52, v68
	s_nop 1
	v_addc_co_u32_e32 v115, vcc, 0, v69, vcc
	global_load_dwordx4 v[120:123], v[114:115], off
	v_add_co_u32_e32 v114, vcc, v52, v66
	s_nop 1
	v_addc_co_u32_e32 v115, vcc, 0, v67, vcc
	global_load_dwordx4 v[124:127], v[114:115], off
	global_load_dwordx4 v[128:131], v[38:39], off
	v_add_co_u32_e32 v114, vcc, v54, v68
	s_nop 1
	v_addc_co_u32_e32 v115, vcc, 0, v69, vcc
	global_load_dwordx4 v[132:135], v[114:115], off
	v_add_co_u32_e32 v114, vcc, v54, v66
	s_nop 1
	v_addc_co_u32_e32 v115, vcc, 0, v67, vcc
	global_load_dwordx4 v[136:139], v[114:115], off
	global_load_dwordx4 v[140:143], v[40:41], off
	v_add_co_u32_e32 v114, vcc, v56, v68
	s_nop 1
	v_addc_co_u32_e32 v115, vcc, 0, v69, vcc
	global_load_dwordx4 v[144:147], v[114:115], off
	v_add_co_u32_e32 v114, vcc, v56, v66
	s_nop 1
	v_addc_co_u32_e32 v115, vcc, 0, v67, vcc
	global_load_dwordx4 v[148:151], v[114:115], off
	global_load_dwordx4 v[152:155], v[42:43], off
	v_add_co_u32_e32 v114, vcc, v58, v68
	s_nop 1
	v_addc_co_u32_e32 v115, vcc, 0, v69, vcc
	global_load_dwordx4 v[156:159], v[114:115], off
	v_add_co_u32_e32 v114, vcc, v58, v66
	s_nop 1
	v_addc_co_u32_e32 v115, vcc, 0, v67, vcc
	global_load_dwordx4 v[160:163], v[114:115], off
	global_load_dwordx4 v[164:167], v[44:45], off
	v_add_co_u32_e32 v114, vcc, v60, v68
	s_nop 1
	v_addc_co_u32_e32 v115, vcc, 0, v69, vcc
	global_load_dwordx4 v[168:171], v[114:115], off
	v_add_co_u32_e32 v114, vcc, v60, v66
	s_nop 1
	v_addc_co_u32_e32 v115, vcc, 0, v67, vcc
	global_load_dwordx4 v[172:175], v[114:115], off
	global_load_dwordx4 v[176:179], v[46:47], off
	v_add_co_u32_e32 v114, vcc, v62, v68
	s_nop 1
	v_addc_co_u32_e32 v115, vcc, 0, v69, vcc
	global_load_dwordx4 v[180:183], v[114:115], off
	v_add_co_u32_e32 v114, vcc, v62, v66
	s_nop 1
	v_addc_co_u32_e32 v115, vcc, 0, v67, vcc
	global_load_dwordx4 v[184:187], v[114:115], off
	global_load_dwordx4 v[188:191], v[48:49], off
	v_add_co_u32_e32 v114, vcc, v64, v68
	s_nop 1
	v_addc_co_u32_e32 v115, vcc, 0, v69, vcc
	global_load_dwordx4 v[192:195], v[114:115], off
	v_add_co_u32_e32 v114, vcc, v64, v66
	s_nop 1
	v_addc_co_u32_e32 v115, vcc, 0, v67, vcc
	global_load_dwordx4 v[196:199], v[114:115], off
	v_lshlrev_b64 v[70:71], 12, v[70:71]
	v_lshl_add_u64 v[70:71], v[32:33], 0, v[70:71]
	v_lshl_add_u64 v[28:29], v[28:29], 0, s[86:87]
	v_lshl_add_u64 v[50:51], v[50:51], 0, s[16:17]
	s_waitcnt vmcnt(31)
	v_mul_f32_e32 v53, v81, v81
	s_waitcnt vmcnt(30)
	v_mul_f32_e32 v55, v25, v25
	s_waitcnt vmcnt(29)
	v_mul_f32_e32 v57, v21, v21
	v_fmac_f32_e32 v53, v80, v80
	v_fmac_f32_e32 v55, v24, v24
	s_waitcnt vmcnt(28)
	v_mul_f32_e32 v59, v17, v17
	v_fmac_f32_e32 v57, v20, v20
	s_waitcnt vmcnt(27)
	v_mov_b32_e32 v100, v13
	s_waitcnt vmcnt(26)
	v_mov_b32_e32 v101, v9
	v_fmac_f32_e32 v53, v82, v82
	v_fmac_f32_e32 v55, v26, v26
	v_fmac_f32_e32 v59, v16, v16
	v_mov_b32_e32 v98, v12
	v_mov_b32_e32 v99, v8
	v_fmac_f32_e32 v57, v22, v22
	v_pk_mul_f32 v[100:101], v[100:101], v[100:101]
	v_fmac_f32_e32 v53, v83, v83
	v_fmac_f32_e32 v55, v27, v27
	v_mov_b32_e32 v102, v14
	v_mov_b32_e32 v103, v10
	s_waitcnt vmcnt(25)
	v_mov_b32_e32 v108, v5
	s_waitcnt vmcnt(24)
	v_mov_b32_e32 v109, v1
	v_fmac_f32_e32 v59, v18, v18
	v_fmac_f32_e32 v57, v23, v23
	v_pk_fma_f32 v[98:99], v[98:99], v[98:99], v[100:101]
	v_add_f32_e32 v53, v53, v55
	v_mov_b32_e32 v104, v15
	v_mov_b32_e32 v105, v11
	v_mov_b32_e32 v106, v4
	v_mov_b32_e32 v107, v0
	v_pk_mul_f32 v[108:109], v[108:109], v[108:109]
	v_fmac_f32_e32 v59, v19, v19
	v_pk_fma_f32 v[98:99], v[102:103], v[102:103], v[98:99]
	v_add_f32_e32 v53, v53, v57
	v_mov_b32_e32 v110, v6
	v_mov_b32_e32 v111, v2
	v_pk_fma_f32 v[100:101], v[106:107], v[106:107], v[108:109]
	v_pk_fma_f32 v[98:99], v[104:105], v[104:105], v[98:99]
	v_add_f32_e32 v53, v53, v59
	v_mov_b32_e32 v112, v7
	v_mov_b32_e32 v113, v3
	v_pk_fma_f32 v[100:101], v[110:111], v[110:111], v[100:101]
	v_add_f32_e32 v53, v53, v98
	v_pk_fma_f32 v[100:101], v[112:113], v[112:113], v[100:101]
	v_add_f32_e32 v53, v53, v99
	v_add_f32_e32 v53, v53, v100
	v_add_f32_e32 v53, v53, v101
	ds_bpermute_b32 v55, v72, v53
	s_waitcnt vmcnt(21)
	v_add_f32_e32 v59, 1.0, v94
	v_add_f32_e32 v61, 1.0, v95
	s_waitcnt lgkmcnt(0)
	v_add_f32_e32 v53, v53, v55
	ds_bpermute_b32 v55, v73, v53
	s_waitcnt lgkmcnt(0)
	v_add_f32_e32 v53, v53, v55
	ds_bpermute_b32 v55, v74, v53
	s_waitcnt lgkmcnt(0)
	v_add_f32_e32 v53, v53, v55
	ds_bpermute_b32 v55, v75, v53
	s_waitcnt lgkmcnt(0)
; __device__ __forceinline__ unsigned cvt_pk_bf16(float lo, float hi) { unsigned r; asm("v_cvt_pk_bf16_f32 %0, %1, %2" : "=v"(r) : "v"(lo), "v"(hi)); return r; }
; __device__ __forceinline__ void xn_row(const float* hrow, const float* g, const float* shift, const float* scale, bf16_t* orow, int lane) {
;     ...
;     const float r = rsqrtf(wave_sum(s) * (1.f / D) + 1e-6f);
;     u32x2* o = (u32x2*)orow + lane;
; #pragma unroll
;     for (int j = 0; j < 8; ++j) { const float4 gg = ((const float4*)g)[lane + 64 * j], sh = ((const float4*)shift)[lane + 64 * j], sc = ((const float4*)scale)[lane + 64 * j];
;         u32x2 w; w.x = cvt_pk_bf16(v[j].x * r * gg.x * (1.f + sc.x) + sh.x, v[j].y * r * gg.y * (1.f + sc.y) + sh.y);
;         w.y = cvt_pk_bf16(v[j].z * r * gg.z * (1.f + sc.z) + sh.z, v[j].w * r * gg.w * (1.f + sc.w) + sh.w);
;         o[64 * j] = w; }
	v_add_f32_e32 v53, v53, v55
	ds_bpermute_b32 v55, v76, v53
	s_waitcnt lgkmcnt(0)
	v_add_f32_e32 v55, v53, v55
	ds_bpermute_b32 v57, v77, v55
	v_mov_b32_e32 v53, v31
	v_lshl_add_u64 v[98:99], v[68:69], 0, v[52:53]
	v_add_f32_e32 v53, 1.0, v92
	s_waitcnt lgkmcnt(0)
	v_add_f32_e32 v55, v55, v57
	v_fmamk_f32 v55, v55, 0x3a000000, v78
	v_mul_f32_e32 v57, 0x4b800000, v55
	v_cmp_gt_f32_e32 vcc, s12, v55
	s_nop 1
	v_cndmask_b32_e32 v55, v55, v57, vcc
	v_rsq_f32_e32 v55, v55
	v_add_f32_e32 v57, 1.0, v93
	v_mul_f32_e32 v63, 0x45800000, v55
	v_cndmask_b32_e32 v79, v55, v63, vcc
	v_mul_f32_e32 v55, v80, v79
	v_mul_f32_e32 v63, v81, v79
	v_mul_f32_e32 v65, v82, v79
	v_mul_f32_e32 v80, v83, v79
	v_mul_f32_e32 v55, v84, v55
	v_mul_f32_e32 v63, v85, v63
	v_mul_f32_e32 v65, v86, v65
	v_mul_f32_e32 v80, v87, v80
	v_fma_f32 v53, v53, v55, v88
	v_fma_f32 v55, v57, v63, v89
	v_fma_f32 v57, v65, v59, v90
	v_fmac_f32_e32 v91, v80, v61
	v_cvt_pk_bf16_f32 v80, v53, v55
	v_cvt_pk_bf16_f32 v81, v57, v91
	global_store_dwordx2 v[70:71], v[80:81], off
	v_mov_b32_e32 v55, v31
	v_mov_b32_e32 v61, v31
	v_mov_b32_e32 v63, v31
	v_mov_b32_e32 v65, v31
	v_cmp_lt_i32_e32 vcc, s13, v28
	s_or_b64 s[18:19], vcc, s[18:19]
	v_mov_b32_e32 v57, v31
	v_mov_b32_e32 v59, v31
	v_mul_f32_e32 v24, v24, v79
	v_mul_f32_e32 v25, v25, v79
	v_mul_f32_e32 v26, v26, v79
	v_mul_f32_e32 v27, v27, v79
	v_mul_f32_e32 v20, v20, v79
	v_mul_f32_e32 v21, v21, v79
	v_mul_f32_e32 v22, v22, v79
	v_mul_f32_e32 v23, v23, v79
	v_mul_f32_e32 v16, v16, v79
	v_mul_f32_e32 v17, v17, v79
	v_mul_f32_e32 v18, v18, v79
	v_mul_f32_e32 v19, v19, v79
	v_mul_f32_e32 v12, v12, v79
	v_mul_f32_e32 v13, v13, v79
	v_mul_f32_e32 v14, v14, v79
	v_mul_f32_e32 v15, v15, v79
	v_mul_f32_e32 v8, v8, v79
	v_mul_f32_e32 v9, v9, v79
	v_mul_f32_e32 v10, v10, v79
	v_mul_f32_e32 v11, v11, v79
	v_mul_f32_e32 v4, v4, v79
	v_mul_f32_e32 v5, v5, v79
	v_mul_f32_e32 v6, v6, v79
	v_mul_f32_e32 v7, v7, v79
	v_mul_f32_e32 v0, v0, v79
	v_mul_f32_e32 v1, v1, v79
	v_mul_f32_e32 v2, v2, v79
	v_mul_f32_e32 v3, v3, v79
	s_waitcnt vmcnt(18)
	v_mul_f32_e32 v24, v24, v116
	v_mul_f32_e32 v25, v25, v117
	v_mul_f32_e32 v26, v26, v118
	v_mul_f32_e32 v27, v27, v119
	v_add_f32_e32 v120, 1.0, v120
	v_add_f32_e32 v121, 1.0, v121
	v_add_f32_e32 v122, 1.0, v122
	v_add_f32_e32 v123, 1.0, v123
	v_fma_f32 v24, v24, v120, v124
	v_fma_f32 v25, v25, v121, v125
	v_fma_f32 v26, v26, v122, v126
	v_fma_f32 v27, v27, v123, v127
	v_cvt_pk_bf16_f32 v24, v24, v25
	v_cvt_pk_bf16_f32 v25, v26, v27
	global_store_dwordx2 v[70:71], v[24:25], off offset:512
	s_waitcnt vmcnt(15)
	v_mul_f32_e32 v20, v20, v128
	v_mul_f32_e32 v21, v21, v129
	v_mul_f32_e32 v22, v22, v130
	v_mul_f32_e32 v23, v23, v131
	v_add_f32_e32 v132, 1.0, v132
	v_add_f32_e32 v133, 1.0, v133
	v_add_f32_e32 v134, 1.0, v134
	v_add_f32_e32 v135, 1.0, v135
	v_fma_f32 v20, v20, v132, v136
	v_fma_f32 v21, v21, v133, v137
	v_fma_f32 v22, v22, v134, v138
	v_fma_f32 v23, v23, v135, v139
	v_cvt_pk_bf16_f32 v20, v20, v21
	v_cvt_pk_bf16_f32 v21, v22, v23
	global_store_dwordx2 v[70:71], v[20:21], off offset:1024
	s_waitcnt vmcnt(12)
	v_mul_f32_e32 v16, v16, v140
	v_mul_f32_e32 v17, v17, v141
	v_mul_f32_e32 v18, v18, v142
	v_mul_f32_e32 v19, v19, v143
	v_add_f32_e32 v144, 1.0, v144
	v_add_f32_e32 v145, 1.0, v145
	v_add_f32_e32 v146, 1.0, v146
	v_add_f32_e32 v147, 1.0, v147
	v_fma_f32 v16, v16, v144, v148
	v_fma_f32 v17, v17, v145, v149
	v_fma_f32 v18, v18, v146, v150
	v_fma_f32 v19, v19, v147, v151
	v_cvt_pk_bf16_f32 v16, v16, v17
	v_cvt_pk_bf16_f32 v17, v18, v19
	global_store_dwordx2 v[70:71], v[16:17], off offset:1536
	s_waitcnt vmcnt(9)
	v_mul_f32_e32 v12, v12, v152
	v_mul_f32_e32 v13, v13, v153
	v_mul_f32_e32 v14, v14, v154
	v_mul_f32_e32 v15, v15, v155
	v_add_f32_e32 v156, 1.0, v156
	v_add_f32_e32 v157, 1.0, v157
	v_add_f32_e32 v158, 1.0, v158
	v_add_f32_e32 v159, 1.0, v159
	v_fma_f32 v12, v12, v156, v160
	v_fma_f32 v13, v13, v157, v161
	v_fma_f32 v14, v14, v158, v162
	v_fma_f32 v15, v15, v159, v163
	v_cvt_pk_bf16_f32 v12, v12, v13
	v_cvt_pk_bf16_f32 v13, v14, v15
	global_store_dwordx2 v[70:71], v[12:13], off offset:2048
	s_waitcnt vmcnt(6)
	v_mul_f32_e32 v8, v8, v164
	v_mul_f32_e32 v9, v9, v165
	v_mul_f32_e32 v10, v10, v166
	v_mul_f32_e32 v11, v11, v167
	v_add_f32_e32 v168, 1.0, v168
	v_add_f32_e32 v169, 1.0, v169
	v_add_f32_e32 v170, 1.0, v170
	v_add_f32_e32 v171, 1.0, v171
	v_fma_f32 v8, v8, v168, v172
	v_fma_f32 v9, v9, v169, v173
	v_fma_f32 v10, v10, v170, v174
	v_fma_f32 v11, v11, v171, v175
	v_cvt_pk_bf16_f32 v8, v8, v9
	v_cvt_pk_bf16_f32 v9, v10, v11
	global_store_dwordx2 v[70:71], v[8:9], off offset:2560
	s_waitcnt vmcnt(3)
	v_mul_f32_e32 v4, v4, v176
	v_mul_f32_e32 v5, v5, v177
	v_mul_f32_e32 v6, v6, v178
	v_mul_f32_e32 v7, v7, v179
	v_add_f32_e32 v180, 1.0, v180
	v_add_f32_e32 v181, 1.0, v181
	v_add_f32_e32 v182, 1.0, v182
	v_add_f32_e32 v183, 1.0, v183
	v_fma_f32 v4, v4, v180, v184
	v_fma_f32 v5, v5, v181, v185
	v_fma_f32 v6, v6, v182, v186
	v_fma_f32 v7, v7, v183, v187
	v_cvt_pk_bf16_f32 v4, v4, v5
	v_cvt_pk_bf16_f32 v5, v6, v7
	global_store_dwordx2 v[70:71], v[4:5], off offset:3072
	s_waitcnt vmcnt(0)
	v_mul_f32_e32 v0, v0, v188
	v_mul_f32_e32 v1, v1, v189
	v_mul_f32_e32 v2, v2, v190
	v_mul_f32_e32 v3, v3, v191
	v_add_f32_e32 v192, 1.0, v192
	v_add_f32_e32 v193, 1.0, v193
	v_add_f32_e32 v194, 1.0, v194
	v_add_f32_e32 v195, 1.0, v195
	v_fma_f32 v0, v0, v192, v196
	v_fma_f32 v1, v1, v193, v197
	v_fma_f32 v2, v2, v194, v198
	v_fma_f32 v3, v3, v195, v199
	v_cvt_pk_bf16_f32 v0, v0, v1
	v_cvt_pk_bf16_f32 v1, v2, v3
	global_store_dwordx2 v[70:71], v[0:1], off offset:3584
	s_andn2_b64 exec, exec, s[18:19]
	s_cbranch_execz .LBB0_770

; __device__ __forceinline__ int otid() { int t = (int)__builtin_amdgcn_workitem_id_x(); asm volatile("" : "+v"(t)); return t; }
; __device__ __forceinline__ void s5inc_item(PRef p, int item, unsigned char* shm) {
;     const int tid = otid(), lane = tid & 63, wave = tid >> 6, fr = lane & 15, fq = lane >> 4;
;     const int g = item >> 3, dir = (item >> 2) & 1, b = item & 3;
;     const bf16_t* A = (const bf16_t*)(p.ws + O_A);
;     const bf16_t* E = (const bf16_t*)(p.ws + O_S5E) + ((size_t)(dir * 32 + g) * 128 + 16 * wave + fr) * 1024 + fq * 8;
;     bf16x8 af[32];
; #pragma unroll
;     for (int kk = 0; kk < 32; ++kk) af[kk] = *(const bf16x8*)(E + kk * 32);
;     float* ST = (float*)(p.ws + O_S5ST) + (size_t)((g * 2 + dir) * 4 + b) * 68 * 128;
.LBB0_815:
	s_and_b64 vcc, exec, s[4:5]
	s_cbranch_vccz .LBB0_809
	s_and_b32 s99, s39, 7
	s_lshl_b32 s99, s99, 2
	s_lshr_b32 s100, s39, 6
	s_add_i32 s99, s99, s100
	s_lshl_b32 s99, s99, 3
	s_bfe_u32 s100, s39, 0x30003
	s_or_b32 s99, s99, s100
	s_bfe_u32 s6, s99, 0x10002
	s_ashr_i32 s22, s99, 3
	s_lshl_b32 s4, s6, 5
	v_mov_b32_e32 v134, v222
	s_add_i32 s4, s4, s22
	s_ashr_i32 s5, s4, 31
	v_ashrrev_i32_e32 v0, 2, v134
	v_and_b32_e32 v128, -16, v0
	s_lshl_b64 s[4:5], s[4:5], 7
	v_ashrrev_i32_e32 v129, 31, v128
	v_and_b32_e32 v147, 15, v134
	v_lshl_add_u64 v[0:1], s[4:5], 0, v[128:129]
	v_or_b32_e32 v0, v0, v147
	v_lshlrev_b64 v[0:1], 11, v[0:1]
	v_lshl_add_u64 v[0:1], s[20:21], 0, v[0:1]
	v_and_b32_e32 v130, 48, v134
	v_mov_b32_e32 v131, v133
	v_lshl_add_u64 v[124:125], v[0:1], 0, v[130:131]
	global_load_dwordx4 v[0:3], v[124:125], off
	global_load_dwordx4 v[4:7], v[124:125], off offset:64
	global_load_dwordx4 v[8:11], v[124:125], off offset:128
	global_load_dwordx4 v[12:15], v[124:125], off offset:192
	global_load_dwordx4 v[16:19], v[124:125], off offset:256
	global_load_dwordx4 v[20:23], v[124:125], off offset:320
	global_load_dwordx4 v[24:27], v[124:125], off offset:384
	global_load_dwordx4 v[28:31], v[124:125], off offset:448
	global_load_dwordx4 v[32:35], v[124:125], off offset:512
	global_load_dwordx4 v[36:39], v[124:125], off offset:576
	global_load_dwordx4 v[40:43], v[124:125], off offset:640
	global_load_dwordx4 v[44:47], v[124:125], off offset:704
	global_load_dwordx4 v[48:51], v[124:125], off offset:768
	global_load_dwordx4 v[52:55], v[124:125], off offset:832
	global_load_dwordx4 v[56:59], v[124:125], off offset:896
	global_load_dwordx4 v[60:63], v[124:125], off offset:960
	global_load_dwordx4 v[64:67], v[124:125], off offset:1024
	global_load_dwordx4 v[68:71], v[124:125], off offset:1088
	global_load_dwordx4 v[72:75], v[124:125], off offset:1152
	global_load_dwordx4 v[76:79], v[124:125], off offset:1216
	global_load_dwordx4 v[80:83], v[124:125], off offset:1280
	global_load_dwordx4 v[84:87], v[124:125], off offset:1344
	global_load_dwordx4 v[88:91], v[124:125], off offset:1408
	global_load_dwordx4 v[92:95], v[124:125], off offset:1472
	global_load_dwordx4 v[96:99], v[124:125], off offset:1536
	global_load_dwordx4 v[100:103], v[124:125], off offset:1600
	global_load_dwordx4 v[104:107], v[124:125], off offset:1664
	global_load_dwordx4 v[108:111], v[124:125], off offset:1728
	global_load_dwordx4 v[112:115], v[124:125], off offset:1792
	global_load_dwordx4 v[116:119], v[124:125], off offset:1856
	global_load_dwordx4 v[120:123], v[124:125], off offset:1920
	s_nop 0
	global_load_dwordx4 v[124:127], v[124:125], off offset:1984
	s_and_b32 s4, s99, 3
	s_and_b32 s5, s99, -8
	s_lshl_b32 s6, s6, 2
	s_lshl_b32 s26, s4, 12
	s_and_b32 s4, s99, 3
	s_or_b32 s5, s6, s5
	v_ashrrev_i32_e32 v149, 7, v134
	s_or_b32 s5, s5, s4
	v_lshlrev_b32_e32 v156, 6, v149
	v_mul_lo_u32 v157, v149, s37
	v_add_u32_e32 v149, 0x200, v134
	s_mul_hi_i32 s7, s5, 0x8800
	s_mul_i32 s5, s5, 0x8800
	v_and_b32_e32 v135, 1, v134
	v_bfe_u32 v155, v134, 1, 6
	v_ashrrev_i32_e32 v150, 7, v149
	s_add_u32 s6, s14, s5
	v_lshlrev_b32_e32 v132, 3, v135
	v_lshlrev_b32_e32 v148, 5, v155
	v_lshlrev_b32_e32 v135, 4, v135
	v_lshlrev_b32_e32 v154, 6, v150
	v_mul_lo_u32 v158, v150, s37
	v_add_u32_e32 v150, 0x400, v134
	v_add_u32_e32 v134, 0x600, v134
	s_addc_u32 s7, s28, s7
	v_add3_u32 v159, 0, v148, v135
	v_lshl_or_b32 v135, s4, 8, v155
	v_ashrrev_i32_e32 v151, 7, v150
	v_ashrrev_i32_e32 v134, 7, v134
	v_or_b32_e32 v135, 0x4000, v135
	v_lshlrev_b32_e32 v153, 6, v151
	v_lshlrev_b32_e32 v152, 6, v134
	v_lshl_add_u64 v[128:129], v[128:129], 2, s[6:7]
	v_and_or_b32 v148, v156, s36, v135
	v_and_or_b32 v149, v154, s36, v135
	v_and_or_b32 v150, v153, s36, v135
	v_mul_lo_u32 v160, v151, s37
	v_and_or_b32 v151, v152, s36, v135
	v_mul_lo_u32 v161, v134, s37
	v_lshl_add_u64 v[134:135], v[128:129], 0, v[130:131]
	v_add_u32_e32 v128, s26, v152
	v_or_b32_e32 v152, v128, v155
	v_add_u32_e32 v128, s26, v153
	s_lshl_b32 s24, s22, 4
	v_or_b32_e32 v153, v128, v155
	v_add_u32_e32 v128, s26, v154
	s_ashr_i32 s25, s24, 31
	v_mad_u32_u24 v162, v147, s37, 0
	v_or_b32_e32 v154, v128, v155
	v_add_u32_e32 v128, s26, v156
	s_mov_b32 s12, 4
	v_cmp_gt_u32_e64 s[4:5], 4, v147
	v_or_b32_e32 v155, v128, v155
	s_mov_b32 s22, 0
	s_lshl_b64 s[24:25], s[24:25], 1
	v_lshlrev_b32_e32 v132, 1, v132
	v_add_u32_e32 v156, v159, v157
	v_add_u32_e32 v157, v159, v158
	v_add_u32_e32 v158, v159, v160
	v_add_u32_e32 v159, v159, v161
	v_add_u32_e32 v160, v162, v130
	s_branch .LBB0_818

; __device__ __forceinline__ int otid() { int t = (int)__builtin_amdgcn_workitem_id_x(); asm volatile("" : "+v"(t)); return t; }
; __device__ __forceinline__ void s5out_item(PRef p, int layer, int item, unsigned char* shm) {
;     const int tid = otid(), lane = tid & 63, wave = tid >> 6, fr = lane & 15, fq = lane >> 4;
;     const int g = item >> 3, b = (item >> 1) & 3, mh = item & 1;
;     const bf16_t* A = (const bf16_t*)(p.ws + O_A);
;     bf16_t* KT = (bf16_t*)shm;
;     unsigned char* ul = shm + 65024;
;     __syncthreads();
;     { const u32x4* src = (const u32x4*)((const bf16_t*)(p.ws + O_S5K) + (size_t)g * 127 * 256); u32x4* dst = (u32x4*)shm;
;       for (int i = tid; i < 127 * 256 / 8; i += 512) dst[i] = src[i]; }
;     const int tb = 32 * mh + 4 * wave;
;     bf16_t* Z = (bf16_t*)(p.ws + O_Z5);
;     const f32x4 dv = *(const f32x4*)(p.in[25] + layer * 512 + g * 16 + fq * 4);
.LBB0_923:
	s_and_b64 vcc, exec, s[34:35]
	s_cbranch_vccz .LBB0_918
	s_and_b32 s99, s61, 7
	s_lshl_b32 s99, s99, 2
	s_lshr_b32 s100, s61, 6
	s_add_i32 s99, s99, s100
	s_lshl_b32 s99, s99, 3
	s_bfe_u32 s100, s61, 0x30003
	s_or_b32 s99, s99, s100
	s_ashr_i32 s38, s99, 3
	v_mov_b32_e32 v4, v222
	s_ashr_i32 s39, s38, 31
	s_nop 0
	v_cmp_gt_i32_e32 vcc, s57, v4
	s_barrier
	s_and_saveexec_b64 s[34:35], vcc
	s_cbranch_execz .LBB0_927
	s_mul_i32 s20, s38, 0xfe00
	s_mul_hi_i32 s12, s38, 0xfe00
	s_add_u32 s36, s42, s20
	v_ashrrev_i32_e32 v5, 31, v4
	s_addc_u32 s37, s43, s12
	v_add_u32_e32 v2, 0xfffffe00, v4
	v_lshl_add_u32 v3, v4, 4, 0
	v_lshl_add_u64 v[0:1], v[4:5], 4, s[36:37]
	s_mov_b64 s[36:37], 0
.LBB0_926:
	global_load_dwordx4 v[6:9], v[0:1], off
	v_lshl_add_u64 v[0:1], v[0:1], 0, s[22:23]
	global_load_dwordx4 v[148:151], v[0:1], off
	v_lshl_add_u64 v[0:1], v[0:1], 0, s[22:23]
	global_load_dwordx4 v[152:155], v[0:1], off
	v_lshl_add_u64 v[0:1], v[0:1], 0, s[22:23]
	global_load_dwordx4 v[156:159], v[0:1], off
	v_lshl_add_u64 v[0:1], v[0:1], 0, s[22:23]
	global_load_dwordx4 v[160:163], v[0:1], off
	v_lshl_add_u64 v[0:1], v[0:1], 0, s[22:23]
	global_load_dwordx4 v[164:167], v[0:1], off
	v_lshl_add_u64 v[0:1], v[0:1], 0, s[22:23]
	global_load_dwordx4 v[168:171], v[0:1], off
	v_lshl_add_u64 v[0:1], v[0:1], 0, s[22:23]
	v_add_u32_e32 v2, 0xe00, v2
	v_cmp_lt_i32_e32 vcc, s58, v2
	s_mov_b64 s[36:37], exec
	s_andn2_b64 exec, exec, vcc
	global_load_dwordx4 v[172:175], v[0:1], off
	s_mov_b64 exec, s[36:37]
	s_waitcnt vmcnt(7)
	ds_write_b128 v3, v[6:9]
	v_add_u32_e32 v3, 0x2000, v3
	s_waitcnt vmcnt(6)
	ds_write_b128 v3, v[148:151]
	v_add_u32_e32 v3, 0x2000, v3
	s_waitcnt vmcnt(5)
	ds_write_b128 v3, v[152:155]
	v_add_u32_e32 v3, 0x2000, v3
	s_waitcnt vmcnt(4)
	ds_write_b128 v3, v[156:159]
	v_add_u32_e32 v3, 0x2000, v3
	s_waitcnt vmcnt(3)
	ds_write_b128 v3, v[160:163]
	v_add_u32_e32 v3, 0x2000, v3
	s_waitcnt vmcnt(2)
	ds_write_b128 v3, v[164:167]
	v_add_u32_e32 v3, 0x2000, v3
	s_waitcnt vmcnt(1)
	ds_write_b128 v3, v[168:171]
	v_add_u32_e32 v3, 0x2000, v3
	s_waitcnt vmcnt(0)
	s_andn2_b64 exec, exec, vcc
	ds_write_b128 v3, v[172:175]
	s_mov_b64 exec, s[36:37]
.LBB0_927:
	s_or_b64 exec, exec, s[34:35]
	s_lshl_b32 s34, s38, 4
	s_lshl_b32 s20, s99, 5
	s_ashr_i32 s35, s34, 31
	s_bfe_u32 s12, s99, 0x20001
	s_and_b32 s20, s20, 32
	s_lshl_b64 s[36:37], s[34:35], 2
	s_add_u32 s62, s8, s36
	v_bfe_u32 v7, v4, 4, 2
	v_ashrrev_i32_e32 v9, 4, v4
	s_addc_u32 s63, s9, s37
	v_and_b32_e32 v0, -4, v9
	v_lshlrev_b32_e32 v6, 4, v7
	v_add_u32_e32 v75, s20, v0
	global_load_dwordx4 v[0:3], v6, s[62:63] offset:2048
	v_and_b32_e32 v10, 1, v4
	v_bfe_u32 v11, v4, 1, 6
	v_lshlrev_b32_e32 v8, 3, v10
	v_lshlrev_b32_e32 v12, 5, v11
	v_lshlrev_b32_e32 v10, 4, v10
	v_add3_u32 v22, 0, v12, v10
	v_ashrrev_i32_e32 v10, 7, v4
	v_lshlrev_b32_e32 v77, 6, v10
	v_mul_lo_u32 v23, v10, s59
	v_add_u32_e32 v10, 0x200, v4
	v_ashrrev_i32_e32 v10, 7, v10
	s_and_b32 s36, s99, -8
	v_lshlrev_b32_e32 v78, 6, v10
	v_mul_lo_u32 v24, v10, s59
	v_add_u32_e32 v10, 0x400, v4
	s_lshl_b32 s70, s12, 12
	s_or_b32 s12, s12, s36
	s_lshl_b64 s[34:35], s[34:35], 1
	v_ashrrev_i32_e32 v10, 7, v10
	s_add_u32 s64, s28, s34
	v_lshlrev_b32_e32 v79, 6, v10
	v_mul_lo_u32 v25, v10, s59
	v_add_u32_e32 v10, 0x600, v4
	s_addc_u32 s65, s29, s35
	s_mul_hi_i32 s37, s12, 0x8800
	s_mul_i32 s36, s12, 0x8800
	s_or_b32 s12, s12, 4
	v_and_b32_e32 v5, 15, v4
	v_ashrrev_i32_e32 v10, 7, v10
	s_lshl_b64 s[66:67], s[38:39], 18
	s_lshl_b64 s[68:69], s[38:39], 18
	s_mul_hi_i32 s39, s12, 0x8800
	s_mul_i32 s38, s12, 0x8800
	s_mul_i32 s12, s99, 32
	v_or_b32_e32 v76, s70, v11
	v_lshlrev_b32_e32 v80, 6, v10
	v_mul_lo_u32 v26, v10, s59
	v_mul_u32_u24_e32 v27, 0x810, v5
	v_lshlrev_b32_e32 v32, 3, v7
	v_lshlrev_b32_e32 v10, 5, v7
	v_mov_b32_e32 v11, v33
	v_mov_b32_e32 v7, v33
	v_lshl_or_b32 v14, v75, 4, v5
	s_add_i32 s20, 0, 0xfe00
	s_lshl_b32 s12, s12, 9
	v_lshl_add_u64 v[34:35], s[18:19], 0, v[10:11]
	v_lshl_add_u64 v[10:11], s[16:17], 0, v[6:7]
	v_ashrrev_i32_e32 v15, 31, v14
	v_add3_u32 v86, v27, v6, s20
	v_lshlrev_b32_e32 v6, 9, v9
	s_and_b32 s12, s12, 0x4000
	v_lshlrev_b64 v[16:17], 8, v[14:15]
	v_or_b32_e32 v18, 16, v14
	v_or_b32_e32 v20, 32, v14
	v_or_b32_e32 v14, 48, v14
	v_and_b32_e32 v6, 0xfffff800, v6
	v_lshlrev_b32_e32 v28, 5, v5
	v_lshl_add_u64 v[12:13], v[10:11], 0, s[66:67]
	v_ashrrev_i32_e32 v19, 31, v18
	v_ashrrev_i32_e32 v21, 31, v20
	v_ashrrev_i32_e32 v15, 31, v14
	v_lshl_add_u64 v[10:11], v[10:11], 0, s[68:69]
	v_add_u32_e32 v6, s12, v6
	v_and_b32_e32 v9, 16, v4
	v_lshlrev_b32_e32 v4, 4, v4
	v_lshlrev_b64 v[18:19], 8, v[18:19]
	v_lshlrev_b64 v[20:21], 8, v[20:21]
	v_lshlrev_b64 v[14:15], 8, v[14:15]
	v_lshl_add_u64 v[10:11], v[10:11], 0, s[30:31]
	v_or_b32_e32 v83, 1, v75
	v_or_b32_e32 v84, 2, v75
	v_or_b32_e32 v85, 3, v75
	v_or3_b32 v6, v6, v28, v9
	v_and_b32_e32 v4, 0x200, v4
	v_add_u32_e32 v81, 4, v5
	v_add3_u32 v7, 0, v27, v32
	v_lshl_or_b32 v82, v5, 6, s70
	v_lshl_add_u64 v[38:39], v[12:13], 0, v[16:17]
	v_lshl_add_u64 v[40:41], v[12:13], 0, v[18:19]
	v_lshl_add_u64 v[42:43], v[12:13], 0, v[20:21]
	v_lshl_add_u64 v[44:45], v[12:13], 0, v[14:15]
	v_lshl_add_u64 v[46:47], v[10:11], 0, v[16:17]
	v_lshl_add_u64 v[48:49], v[10:11], 0, v[18:19]
	v_lshl_add_u64 v[50:51], v[10:11], 0, v[20:21]
	v_lshl_add_u64 v[52:53], v[10:11], 0, v[14:15]
	v_lshlrev_b32_e32 v5, 5, v75
	v_lshlrev_b32_e32 v10, 5, v83
	v_lshlrev_b32_e32 v11, 5, v84
	v_lshlrev_b32_e32 v12, 5, v85
	v_sub_u32_e32 v4, v6, v4
	v_lshl_add_u64 v[36:37], s[64:65], 0, v[32:33]
	v_add_u32_e32 v87, 0, v4
	s_mov_b32 s20, 0
	v_lshlrev_b32_e32 v32, 1, v8
	v_add_u32_e32 v88, v22, v23
	v_add_u32_e32 v89, v22, v24
	v_add_u32_e32 v90, v22, v25
	v_add_u32_e32 v91, v22, v26
	v_add_u32_e32 v92, v7, v5
	v_add_u32_e32 v93, v7, v10
	v_add_u32_e32 v94, v7, v11
	v_add_u32_e32 v95, v7, v12
